# SSM pass 2 output loop: only the first token block waits on vmcnt (prefetch + D vector); blocks 1..7 no longer wait for the previous block's store to complete
# baseline (speedup 1.0000x reference)
; __device__ __forceinline__ unsigned cvt_pk_bf16(float lo, float hi) { unsigned r; asm("v_cvt_pk_bf16_f32 %0, %1, %2" : "=v"(r) : "v"(lo), "v"(hi)); return r; }
; __device__ __forceinline__ float bf_lo(unsigned w) { return __uint_as_float(w << 16); }
; __device__ __forceinline__ float bf_hi(unsigned w) { return __uint_as_float(w & 0xffff0000u); }
; template <bool PASS2>
; __device__ __forceinline__ void ssm_phase(const Params& p, const Frame& F0) {
;     ...
;                 for (int t = 0; t < 8; ++t) {
;                     asm volatile("" ::: "memory");
;                     f32x4 y = (f32x4){0.f, 0.f, 0.f, 0.f};
; #pragma unroll
;                     for (int ks = 0; ks < 4; ++ks) y = __builtin_amdgcn_mfma_f32_16x16x32_bf16(frag[(32 + t * 4 + ks) * 64], uf[ks], y, 0, 0, 0);
; #pragma unroll
;                     for (int kap = 0; kap < 4; ++kap) y = __builtin_amdgcn_mfma_f32_16x16x32_bf16(frag[(64 + t * 4 + kap) * 64], hf[kap], y, 0, 0, 0);
;                     if (j < nsub) {
;                         const size_t off = (size_t)(row0 + 8 * j + t) * DSSM + g * 16 + 4 * gq;
;                         const u32x2 uu = uw[t];
;                         const float z0 = gelu_tanh(y[0] + dv[0] * bf_lo(uu.x)), z1 = gelu_tanh(y[1] + dv[1] * bf_hi(uu.x)), z2 = gelu_tanh(y[2] + dv[2] * bf_lo(uu.y)), z3 = gelu_tanh(y[3] + dv[3] * bf_hi(uu.y));
;                         *(u32x2*)(Zb + off) = (u32x2){cvt_pk_bf16(z0, z1), cvt_pk_bf16(z2, z3)};
.LBB0_648:
	s_or_b64 exec, exec, s[26:27]
	s_nop 4
	ds_read_b128 v[88:91], v105 offset:36864
	ds_read_b128 v[204:207], v105 offset:37888
	ds_read_b128 v[208:211], v105 offset:38912
	s_waitcnt lgkmcnt(2)
	v_mfma_f32_16x16x32_bf16 v[88:91], v[88:91], v[56:59], 0
	s_waitcnt lgkmcnt(1)
	v_mfma_f32_16x16x32_bf16 v[88:91], v[204:207], v[52:55], v[88:91]
	ds_read_b128 v[204:207], v105 offset:39936
	s_waitcnt lgkmcnt(1)
	v_mfma_f32_16x16x32_bf16 v[88:91], v[208:211], v[64:67], v[88:91]
	ds_read_b128 v[208:211], v168
	s_waitcnt lgkmcnt(1)
	v_mfma_f32_16x16x32_bf16 v[88:91], v[204:207], v[60:63], v[88:91]
	ds_read_b128 v[204:207], v169
	s_waitcnt lgkmcnt(1)
	v_mfma_f32_16x16x32_bf16 v[88:91], v[208:211], v[72:75], v[88:91]
	ds_read_b128 v[208:211], v170
	s_waitcnt lgkmcnt(1)
	v_mfma_f32_16x16x32_bf16 v[88:91], v[204:207], v[80:83], v[88:91]
	ds_read_b128 v[204:207], v171
	s_waitcnt lgkmcnt(1)
	v_mfma_f32_16x16x32_bf16 v[88:91], v[208:211], v[68:71], v[88:91]
	s_waitcnt lgkmcnt(0)
	v_mfma_f32_16x16x32_bf16 v[88:91], v[204:207], v[76:79], v[88:91]
	s_and_saveexec_b64 s[26:27], s[24:25]
	s_cbranch_execz .LBB0_650
	v_lshlrev_b32_e32 v1, 16, v154
	s_nop 0
	s_nop 3
	v_fma_f32 v1, v228, v1, v88
	v_and_b32_e32 v88, 0xffff0000, v154
	v_lshlrev_b32_e32 v154, 16, v155
	v_and_b32_e32 v155, 0xffff0000, v155
	v_fma_f32 v88, v229, v88, v89
	v_fma_f32 v90, v230, v154, v90
	v_fmac_f32_e32 v91, v231, v155
	v_mul_f32_e32 v3, v1, v1
	v_mul_f32_e32 v89, v88, v88
	v_mul_f32_e32 v154, v90, v90
	v_mul_f32_e32 v155, v91, v91
	v_fmamk_f32 v3, v3, 0xbdd2d3e8, v93
	v_fmamk_f32 v89, v89, 0xbdd2d3e8, v93
	v_fmamk_f32 v154, v154, 0xbdd2d3e8, v93
	v_fmamk_f32 v155, v155, 0xbdd2d3e8, v93
	v_mul_f32_e32 v3, v1, v3
	v_mul_f32_e32 v89, v88, v89
	v_mul_f32_e32 v154, v90, v154
	v_mul_f32_e32 v155, v91, v155
	v_exp_f32_e32 v3, v3
	v_exp_f32_e32 v89, v89
	v_exp_f32_e32 v154, v154
	v_exp_f32_e32 v155, v155
	v_add_f32_e32 v3, 1.0, v3
	v_add_f32_e32 v89, 1.0, v89
	v_add_f32_e32 v154, 1.0, v154
	v_add_f32_e32 v155, 1.0, v155
	v_rcp_f32_e32 v3, v3
	v_rcp_f32_e32 v89, v89
	v_rcp_f32_e32 v154, v154
	v_rcp_f32_e32 v155, v155
	v_or_b32_e32 v156, 1, v2
	v_ashrrev_i32_e32 v157, 31, v156
	v_mul_f32_e32 v1, v1, v3
	v_mul_f32_e32 v3, v88, v89
	v_mul_f32_e32 v89, v90, v154
	v_mul_f32_e32 v90, v91, v155
	v_cvt_pk_bf16_f32 v89, v89, v90
	v_lshlrev_b64 v[90:91], 10, v[156:157]
	v_lshl_add_u64 v[90:91], v[134:135], 0, v[90:91]
	v_cvt_pk_bf16_f32 v88, v1, v3
	global_store_dwordx2 v[90:91], v[88:89], off
.LBB0_650:
	s_or_b64 exec, exec, s[26:27]
	s_nop 4
	ds_read_b128 v[88:91], v105 offset:40960
	ds_read_b128 v[154:157], v105 offset:41984
	ds_read_b128 v[204:207], v105 offset:43008
	s_waitcnt lgkmcnt(2)
	v_mfma_f32_16x16x32_bf16 v[88:91], v[88:91], v[56:59], 0
	s_waitcnt lgkmcnt(1)
	v_mfma_f32_16x16x32_bf16 v[88:91], v[154:157], v[52:55], v[88:91]
	ds_read_b128 v[154:157], v105 offset:44032
	s_waitcnt lgkmcnt(1)
	v_mfma_f32_16x16x32_bf16 v[88:91], v[204:207], v[64:67], v[88:91]
	ds_read_b128 v[204:207], v172
	s_waitcnt lgkmcnt(1)
	v_mfma_f32_16x16x32_bf16 v[88:91], v[154:157], v[60:63], v[88:91]
	ds_read_b128 v[154:157], v173
	s_waitcnt lgkmcnt(1)
	v_mfma_f32_16x16x32_bf16 v[88:91], v[204:207], v[72:75], v[88:91]
	ds_read_b128 v[204:207], v174
	s_waitcnt lgkmcnt(1)
	v_mfma_f32_16x16x32_bf16 v[88:91], v[154:157], v[80:83], v[88:91]
	ds_read_b128 v[154:157], v175
	s_waitcnt lgkmcnt(1)
	v_mfma_f32_16x16x32_bf16 v[88:91], v[204:207], v[68:71], v[88:91]
	s_waitcnt lgkmcnt(0)
	v_mfma_f32_16x16x32_bf16 v[88:91], v[154:157], v[76:79], v[88:91]
	s_and_saveexec_b64 s[26:27], s[24:25]
	s_cbranch_execz .LBB0_652
	v_lshlrev_b32_e32 v1, 16, v152
	s_nop 0
	s_nop 3
	v_fma_f32 v1, v228, v1, v88
	v_and_b32_e32 v88, 0xffff0000, v152
	v_lshlrev_b32_e32 v152, 16, v153
	v_and_b32_e32 v153, 0xffff0000, v153
	v_fma_f32 v88, v229, v88, v89
	v_fma_f32 v90, v230, v152, v90
	v_fmac_f32_e32 v91, v231, v153
	v_mul_f32_e32 v3, v1, v1
	v_mul_f32_e32 v89, v88, v88
	v_mul_f32_e32 v152, v90, v90
	v_mul_f32_e32 v153, v91, v91
	v_fmamk_f32 v3, v3, 0xbdd2d3e8, v93
	v_fmamk_f32 v89, v89, 0xbdd2d3e8, v93
	v_fmamk_f32 v152, v152, 0xbdd2d3e8, v93
	v_fmamk_f32 v153, v153, 0xbdd2d3e8, v93
	v_mul_f32_e32 v3, v1, v3
	v_mul_f32_e32 v89, v88, v89
	v_mul_f32_e32 v152, v90, v152
	v_mul_f32_e32 v153, v91, v153
	v_exp_f32_e32 v3, v3
	v_exp_f32_e32 v89, v89
	v_exp_f32_e32 v152, v152
	v_exp_f32_e32 v153, v153
	v_add_f32_e32 v3, 1.0, v3
	v_add_f32_e32 v89, 1.0, v89
	v_add_f32_e32 v152, 1.0, v152
	v_add_f32_e32 v153, 1.0, v153
	v_rcp_f32_e32 v3, v3
	v_rcp_f32_e32 v89, v89
	v_rcp_f32_e32 v152, v152
	v_rcp_f32_e32 v153, v153
	v_or_b32_e32 v154, 2, v2
	v_ashrrev_i32_e32 v155, 31, v154
	v_mul_f32_e32 v1, v1, v3
	v_mul_f32_e32 v3, v88, v89
	v_mul_f32_e32 v89, v90, v152
	v_mul_f32_e32 v90, v91, v153
	v_cvt_pk_bf16_f32 v89, v89, v90
	v_lshlrev_b64 v[90:91], 10, v[154:155]
	v_lshl_add_u64 v[90:91], v[134:135], 0, v[90:91]
	v_cvt_pk_bf16_f32 v88, v1, v3
	global_store_dwordx2 v[90:91], v[88:89], off
; __device__ __forceinline__ unsigned cvt_pk_bf16(float lo, float hi) { unsigned r; asm("v_cvt_pk_bf16_f32 %0, %1, %2" : "=v"(r) : "v"(lo), "v"(hi)); return r; }
; __device__ __forceinline__ float bf_lo(unsigned w) { return __uint_as_float(w << 16); }
; __device__ __forceinline__ float bf_hi(unsigned w) { return __uint_as_float(w & 0xffff0000u); }
; template <bool PASS2>
; __device__ __forceinline__ void ssm_phase(const Params& p, const Frame& F0) {
;     ...
;                 for (int t = 0; t < 8; ++t) {
;                     asm volatile("" ::: "memory");
;                     f32x4 y = (f32x4){0.f, 0.f, 0.f, 0.f};
; #pragma unroll
;                     for (int ks = 0; ks < 4; ++ks) y = __builtin_amdgcn_mfma_f32_16x16x32_bf16(frag[(32 + t * 4 + ks) * 64], uf[ks], y, 0, 0, 0);
; #pragma unroll
;                     for (int kap = 0; kap < 4; ++kap) y = __builtin_amdgcn_mfma_f32_16x16x32_bf16(frag[(64 + t * 4 + kap) * 64], hf[kap], y, 0, 0, 0);
;                     if (j < nsub) {
;                         const size_t off = (size_t)(row0 + 8 * j + t) * DSSM + g * 16 + 4 * gq;
;                         const u32x2 uu = uw[t];
;                         const float z0 = gelu_tanh(y[0] + dv[0] * bf_lo(uu.x)), z1 = gelu_tanh(y[1] + dv[1] * bf_hi(uu.x)), z2 = gelu_tanh(y[2] + dv[2] * bf_lo(uu.y)), z3 = gelu_tanh(y[3] + dv[3] * bf_hi(uu.y));
;                         *(u32x2*)(Zb + off) = (u32x2){cvt_pk_bf16(z0, z1), cvt_pk_bf16(z2, z3)};
.LBB0_652:
	s_or_b64 exec, exec, s[26:27]
	s_nop 4
	ds_read_b128 v[88:91], v105 offset:45056
	ds_read_b128 v[152:155], v105 offset:46080
	ds_read_b128 v[204:207], v105 offset:47104
	s_waitcnt lgkmcnt(2)
	v_mfma_f32_16x16x32_bf16 v[88:91], v[88:91], v[56:59], 0
	s_waitcnt lgkmcnt(1)
	v_mfma_f32_16x16x32_bf16 v[88:91], v[152:155], v[52:55], v[88:91]
	ds_read_b128 v[152:155], v105 offset:48128
	s_waitcnt lgkmcnt(1)
	v_mfma_f32_16x16x32_bf16 v[88:91], v[204:207], v[64:67], v[88:91]
	ds_read_b128 v[204:207], v176
	s_waitcnt lgkmcnt(1)
	v_mfma_f32_16x16x32_bf16 v[88:91], v[152:155], v[60:63], v[88:91]
	ds_read_b128 v[152:155], v177
	s_waitcnt lgkmcnt(1)
	v_mfma_f32_16x16x32_bf16 v[88:91], v[204:207], v[72:75], v[88:91]
	ds_read_b128 v[204:207], v178
	s_waitcnt lgkmcnt(1)
	v_mfma_f32_16x16x32_bf16 v[88:91], v[152:155], v[80:83], v[88:91]
	ds_read_b128 v[152:155], v179
	s_waitcnt lgkmcnt(1)
	v_mfma_f32_16x16x32_bf16 v[88:91], v[204:207], v[68:71], v[88:91]
	s_waitcnt lgkmcnt(0)
	v_mfma_f32_16x16x32_bf16 v[88:91], v[152:155], v[76:79], v[88:91]
	s_and_saveexec_b64 s[26:27], s[24:25]
	s_cbranch_execz .LBB0_654
	v_lshlrev_b32_e32 v1, 16, v150
	s_nop 0
	s_nop 3
	v_fma_f32 v1, v228, v1, v88
	v_and_b32_e32 v88, 0xffff0000, v150
	v_lshlrev_b32_e32 v150, 16, v151
	v_and_b32_e32 v151, 0xffff0000, v151
	v_fma_f32 v88, v229, v88, v89
	v_fma_f32 v90, v230, v150, v90
	v_fmac_f32_e32 v91, v231, v151
	v_mul_f32_e32 v3, v1, v1
	v_mul_f32_e32 v89, v88, v88
	v_mul_f32_e32 v150, v90, v90
	v_mul_f32_e32 v151, v91, v91
	v_fmamk_f32 v3, v3, 0xbdd2d3e8, v93
	v_fmamk_f32 v89, v89, 0xbdd2d3e8, v93
	v_fmamk_f32 v150, v150, 0xbdd2d3e8, v93
	v_fmamk_f32 v151, v151, 0xbdd2d3e8, v93
	v_mul_f32_e32 v3, v1, v3
	v_mul_f32_e32 v89, v88, v89
	v_mul_f32_e32 v150, v90, v150
	v_mul_f32_e32 v151, v91, v151
	v_exp_f32_e32 v3, v3
	v_exp_f32_e32 v89, v89
	v_exp_f32_e32 v150, v150
	v_exp_f32_e32 v151, v151
	v_add_f32_e32 v3, 1.0, v3
	v_add_f32_e32 v89, 1.0, v89
	v_add_f32_e32 v150, 1.0, v150
	v_add_f32_e32 v151, 1.0, v151
	v_rcp_f32_e32 v3, v3
	v_rcp_f32_e32 v89, v89
	v_rcp_f32_e32 v150, v150
	v_rcp_f32_e32 v151, v151
	v_or_b32_e32 v152, 3, v2
	v_ashrrev_i32_e32 v153, 31, v152
	v_mul_f32_e32 v1, v1, v3
	v_mul_f32_e32 v3, v88, v89
	v_mul_f32_e32 v89, v90, v150
	v_mul_f32_e32 v90, v91, v151
	v_cvt_pk_bf16_f32 v89, v89, v90
	v_lshlrev_b64 v[90:91], 10, v[152:153]
	v_lshl_add_u64 v[90:91], v[134:135], 0, v[90:91]
	v_cvt_pk_bf16_f32 v88, v1, v3
	global_store_dwordx2 v[90:91], v[88:89], off
.LBB0_654:
	s_or_b64 exec, exec, s[26:27]
	s_nop 4
	ds_read_b128 v[88:91], v105 offset:49152
	ds_read_b128 v[150:153], v105 offset:50176
	ds_read_b128 v[154:157], v105 offset:51200
	s_waitcnt lgkmcnt(2)
	v_mfma_f32_16x16x32_bf16 v[88:91], v[88:91], v[56:59], 0
	s_waitcnt lgkmcnt(1)
	v_mfma_f32_16x16x32_bf16 v[88:91], v[150:153], v[52:55], v[88:91]
	ds_read_b128 v[150:153], v105 offset:52224
	s_waitcnt lgkmcnt(1)
	v_mfma_f32_16x16x32_bf16 v[88:91], v[154:157], v[64:67], v[88:91]
	ds_read_b128 v[154:157], v180
	s_waitcnt lgkmcnt(1)
	v_mfma_f32_16x16x32_bf16 v[88:91], v[150:153], v[60:63], v[88:91]
	ds_read_b128 v[150:153], v181
	s_waitcnt lgkmcnt(1)
	v_mfma_f32_16x16x32_bf16 v[88:91], v[154:157], v[72:75], v[88:91]
	ds_read_b128 v[154:157], v182
	s_waitcnt lgkmcnt(1)
	v_mfma_f32_16x16x32_bf16 v[88:91], v[150:153], v[80:83], v[88:91]
	ds_read_b128 v[150:153], v183
	s_waitcnt lgkmcnt(1)
	v_mfma_f32_16x16x32_bf16 v[88:91], v[154:157], v[68:71], v[88:91]
	s_waitcnt lgkmcnt(0)
	v_mfma_f32_16x16x32_bf16 v[88:91], v[150:153], v[76:79], v[88:91]
	s_and_saveexec_b64 s[26:27], s[24:25]
	s_cbranch_execz .LBB0_656
	v_lshlrev_b32_e32 v1, 16, v148
	s_nop 0
	s_nop 3
	v_fma_f32 v1, v228, v1, v88
	v_and_b32_e32 v88, 0xffff0000, v148
	v_lshlrev_b32_e32 v148, 16, v149
	v_and_b32_e32 v149, 0xffff0000, v149
	v_fma_f32 v88, v229, v88, v89
	v_fma_f32 v90, v230, v148, v90
	v_fmac_f32_e32 v91, v231, v149
	v_mul_f32_e32 v3, v1, v1
	v_mul_f32_e32 v89, v88, v88
	v_mul_f32_e32 v148, v90, v90
	v_mul_f32_e32 v149, v91, v91
	v_fmamk_f32 v3, v3, 0xbdd2d3e8, v93
	v_fmamk_f32 v89, v89, 0xbdd2d3e8, v93
	v_fmamk_f32 v148, v148, 0xbdd2d3e8, v93
	v_fmamk_f32 v149, v149, 0xbdd2d3e8, v93
	v_mul_f32_e32 v3, v1, v3
	v_mul_f32_e32 v89, v88, v89
	v_mul_f32_e32 v148, v90, v148
	v_mul_f32_e32 v149, v91, v149
	v_exp_f32_e32 v3, v3
	v_exp_f32_e32 v89, v89
	v_exp_f32_e32 v148, v148
	v_exp_f32_e32 v149, v149
	v_add_f32_e32 v3, 1.0, v3
	v_add_f32_e32 v89, 1.0, v89
	v_add_f32_e32 v148, 1.0, v148
	v_add_f32_e32 v149, 1.0, v149
	v_rcp_f32_e32 v3, v3
	v_rcp_f32_e32 v89, v89
	v_rcp_f32_e32 v148, v148
	v_rcp_f32_e32 v149, v149
	v_or_b32_e32 v150, 4, v2
	v_ashrrev_i32_e32 v151, 31, v150
	v_mul_f32_e32 v1, v1, v3
	v_mul_f32_e32 v3, v88, v89
	v_mul_f32_e32 v89, v90, v148
	v_mul_f32_e32 v90, v91, v149
	v_cvt_pk_bf16_f32 v89, v89, v90
	v_lshlrev_b64 v[90:91], 10, v[150:151]
	v_lshl_add_u64 v[90:91], v[134:135], 0, v[90:91]
	v_cvt_pk_bf16_f32 v88, v1, v3
	global_store_dwordx2 v[90:91], v[88:89], off
; __device__ __forceinline__ unsigned cvt_pk_bf16(float lo, float hi) { unsigned r; asm("v_cvt_pk_bf16_f32 %0, %1, %2" : "=v"(r) : "v"(lo), "v"(hi)); return r; }
; __device__ __forceinline__ float bf_lo(unsigned w) { return __uint_as_float(w << 16); }
; __device__ __forceinline__ float bf_hi(unsigned w) { return __uint_as_float(w & 0xffff0000u); }
; template <bool PASS2>
; __device__ __forceinline__ void ssm_phase(const Params& p, const Frame& F0) {
;     ...
;                 for (int t = 0; t < 8; ++t) {
;                     asm volatile("" ::: "memory");
;                     f32x4 y = (f32x4){0.f, 0.f, 0.f, 0.f};
; #pragma unroll
;                     for (int ks = 0; ks < 4; ++ks) y = __builtin_amdgcn_mfma_f32_16x16x32_bf16(frag[(32 + t * 4 + ks) * 64], uf[ks], y, 0, 0, 0);
; #pragma unroll
;                     for (int kap = 0; kap < 4; ++kap) y = __builtin_amdgcn_mfma_f32_16x16x32_bf16(frag[(64 + t * 4 + kap) * 64], hf[kap], y, 0, 0, 0);
;                     if (j < nsub) {
;                         const size_t off = (size_t)(row0 + 8 * j + t) * DSSM + g * 16 + 4 * gq;
;                         const u32x2 uu = uw[t];
;                         const float z0 = gelu_tanh(y[0] + dv[0] * bf_lo(uu.x)), z1 = gelu_tanh(y[1] + dv[1] * bf_hi(uu.x)), z2 = gelu_tanh(y[2] + dv[2] * bf_lo(uu.y)), z3 = gelu_tanh(y[3] + dv[3] * bf_hi(uu.y));
;                         *(u32x2*)(Zb + off) = (u32x2){cvt_pk_bf16(z0, z1), cvt_pk_bf16(z2, z3)};
.LBB0_656:
	s_or_b64 exec, exec, s[26:27]
	s_nop 4
	ds_read_b128 v[88:91], v105 offset:53248
	ds_read_b128 v[148:151], v105 offset:54272
	ds_read_b128 v[152:155], v105 offset:55296
	s_waitcnt lgkmcnt(2)
	v_mfma_f32_16x16x32_bf16 v[88:91], v[88:91], v[56:59], 0
	s_waitcnt lgkmcnt(1)
	v_mfma_f32_16x16x32_bf16 v[88:91], v[148:151], v[52:55], v[88:91]
	ds_read_b128 v[148:151], v105 offset:56320
	s_waitcnt lgkmcnt(1)
	v_mfma_f32_16x16x32_bf16 v[88:91], v[152:155], v[64:67], v[88:91]
	ds_read_b128 v[152:155], v184
	s_waitcnt lgkmcnt(1)
	v_mfma_f32_16x16x32_bf16 v[88:91], v[148:151], v[60:63], v[88:91]
	ds_read_b128 v[148:151], v185
	s_waitcnt lgkmcnt(1)
	v_mfma_f32_16x16x32_bf16 v[88:91], v[152:155], v[72:75], v[88:91]
	ds_read_b128 v[152:155], v186
	s_waitcnt lgkmcnt(1)
	v_mfma_f32_16x16x32_bf16 v[88:91], v[148:151], v[80:83], v[88:91]
	ds_read_b128 v[148:151], v187
	s_waitcnt lgkmcnt(1)
	v_mfma_f32_16x16x32_bf16 v[88:91], v[152:155], v[68:71], v[88:91]
	s_waitcnt lgkmcnt(0)
	v_mfma_f32_16x16x32_bf16 v[88:91], v[148:151], v[76:79], v[88:91]
	s_and_saveexec_b64 s[26:27], s[24:25]
	s_cbranch_execz .LBB0_658
	v_lshlrev_b32_e32 v1, 16, v146
	s_nop 0
	s_nop 3
	v_fma_f32 v1, v228, v1, v88
	v_and_b32_e32 v88, 0xffff0000, v146
	v_lshlrev_b32_e32 v146, 16, v147
	v_and_b32_e32 v147, 0xffff0000, v147
	v_fma_f32 v88, v229, v88, v89
	v_fma_f32 v90, v230, v146, v90
	v_fmac_f32_e32 v91, v231, v147
	v_mul_f32_e32 v3, v1, v1
	v_mul_f32_e32 v89, v88, v88
	v_mul_f32_e32 v146, v90, v90
	v_mul_f32_e32 v147, v91, v91
	v_fmamk_f32 v3, v3, 0xbdd2d3e8, v93
	v_fmamk_f32 v89, v89, 0xbdd2d3e8, v93
	v_fmamk_f32 v146, v146, 0xbdd2d3e8, v93
	v_fmamk_f32 v147, v147, 0xbdd2d3e8, v93
	v_mul_f32_e32 v3, v1, v3
	v_mul_f32_e32 v89, v88, v89
	v_mul_f32_e32 v146, v90, v146
	v_mul_f32_e32 v147, v91, v147
	v_exp_f32_e32 v3, v3
	v_exp_f32_e32 v89, v89
	v_exp_f32_e32 v146, v146
	v_exp_f32_e32 v147, v147
	v_add_f32_e32 v3, 1.0, v3
	v_add_f32_e32 v89, 1.0, v89
	v_add_f32_e32 v146, 1.0, v146
	v_add_f32_e32 v147, 1.0, v147
	v_rcp_f32_e32 v3, v3
	v_rcp_f32_e32 v89, v89
	v_rcp_f32_e32 v146, v146
	v_rcp_f32_e32 v147, v147
	v_or_b32_e32 v148, 5, v2
	v_ashrrev_i32_e32 v149, 31, v148
	v_mul_f32_e32 v1, v1, v3
	v_mul_f32_e32 v3, v88, v89
	v_mul_f32_e32 v89, v90, v146
	v_mul_f32_e32 v90, v91, v147
	v_cvt_pk_bf16_f32 v89, v89, v90
	v_lshlrev_b64 v[90:91], 10, v[148:149]
	v_lshl_add_u64 v[90:91], v[134:135], 0, v[90:91]
	v_cvt_pk_bf16_f32 v88, v1, v3
	global_store_dwordx2 v[90:91], v[88:89], off
; __device__ __forceinline__ unsigned cvt_pk_bf16(float lo, float hi) { unsigned r; asm("v_cvt_pk_bf16_f32 %0, %1, %2" : "=v"(r) : "v"(lo), "v"(hi)); return r; }
; __device__ __forceinline__ float bf_lo(unsigned w) { return __uint_as_float(w << 16); }
; __device__ __forceinline__ float bf_hi(unsigned w) { return __uint_as_float(w & 0xffff0000u); }
; template <bool PASS2>
; __device__ __forceinline__ void ssm_phase(const Params& p, const Frame& F0) {
;     ...
;                 for (int t = 0; t < 8; ++t) {
;                     asm volatile("" ::: "memory");
;                     f32x4 y = (f32x4){0.f, 0.f, 0.f, 0.f};
; #pragma unroll
;                     for (int ks = 0; ks < 4; ++ks) y = __builtin_amdgcn_mfma_f32_16x16x32_bf16(frag[(32 + t * 4 + ks) * 64], uf[ks], y, 0, 0, 0);
; #pragma unroll
;                     for (int kap = 0; kap < 4; ++kap) y = __builtin_amdgcn_mfma_f32_16x16x32_bf16(frag[(64 + t * 4 + kap) * 64], hf[kap], y, 0, 0, 0);
;                     if (j < nsub) {
;                         const size_t off = (size_t)(row0 + 8 * j + t) * DSSM + g * 16 + 4 * gq;
;                         const u32x2 uu = uw[t];
;                         const float z0 = gelu_tanh(y[0] + dv[0] * bf_lo(uu.x)), z1 = gelu_tanh(y[1] + dv[1] * bf_hi(uu.x)), z2 = gelu_tanh(y[2] + dv[2] * bf_lo(uu.y)), z3 = gelu_tanh(y[3] + dv[3] * bf_hi(uu.y));
;                         *(u32x2*)(Zb + off) = (u32x2){cvt_pk_bf16(z0, z1), cvt_pk_bf16(z2, z3)};
.LBB0_658:
	s_or_b64 exec, exec, s[26:27]
	s_nop 4
	ds_read_b128 v[88:91], v105 offset:57344
	ds_read_b128 v[146:149], v105 offset:58368
	ds_read_b128 v[150:153], v105 offset:59392
	s_waitcnt lgkmcnt(2)
	v_mfma_f32_16x16x32_bf16 v[88:91], v[88:91], v[56:59], 0
	s_waitcnt lgkmcnt(1)
	v_mfma_f32_16x16x32_bf16 v[88:91], v[146:149], v[52:55], v[88:91]
	ds_read_b128 v[146:149], v105 offset:60416
	s_waitcnt lgkmcnt(1)
	v_mfma_f32_16x16x32_bf16 v[88:91], v[150:153], v[64:67], v[88:91]
	ds_read_b128 v[150:153], v188
	s_waitcnt lgkmcnt(1)
	v_mfma_f32_16x16x32_bf16 v[88:91], v[146:149], v[60:63], v[88:91]
	ds_read_b128 v[146:149], v189
	s_waitcnt lgkmcnt(1)
	v_mfma_f32_16x16x32_bf16 v[88:91], v[150:153], v[72:75], v[88:91]
	ds_read_b128 v[150:153], v190
	s_waitcnt lgkmcnt(1)
	v_mfma_f32_16x16x32_bf16 v[88:91], v[146:149], v[80:83], v[88:91]
	ds_read_b128 v[146:149], v191
	s_waitcnt lgkmcnt(1)
	v_mfma_f32_16x16x32_bf16 v[88:91], v[150:153], v[68:71], v[88:91]
	s_waitcnt lgkmcnt(0)
	v_mfma_f32_16x16x32_bf16 v[88:91], v[146:149], v[76:79], v[88:91]
	s_and_saveexec_b64 s[26:27], s[24:25]
	s_cbranch_execz .LBB0_660
	v_lshlrev_b32_e32 v1, 16, v144
	s_nop 0
	s_nop 3
	v_fma_f32 v1, v228, v1, v88
	v_and_b32_e32 v88, 0xffff0000, v144
	v_lshlrev_b32_e32 v144, 16, v145
	v_and_b32_e32 v145, 0xffff0000, v145
	v_fma_f32 v88, v229, v88, v89
	v_fma_f32 v90, v230, v144, v90
	v_fmac_f32_e32 v91, v231, v145
	v_mul_f32_e32 v3, v1, v1
	v_mul_f32_e32 v89, v88, v88
	v_mul_f32_e32 v144, v90, v90
	v_mul_f32_e32 v145, v91, v91
	v_fmamk_f32 v3, v3, 0xbdd2d3e8, v93
	v_fmamk_f32 v89, v89, 0xbdd2d3e8, v93
	v_fmamk_f32 v144, v144, 0xbdd2d3e8, v93
	v_fmamk_f32 v145, v145, 0xbdd2d3e8, v93
	v_mul_f32_e32 v3, v1, v3
	v_mul_f32_e32 v89, v88, v89
	v_mul_f32_e32 v144, v90, v144
	v_mul_f32_e32 v145, v91, v145
	v_exp_f32_e32 v3, v3
	v_exp_f32_e32 v89, v89
	v_exp_f32_e32 v144, v144
	v_exp_f32_e32 v145, v145
	v_add_f32_e32 v3, 1.0, v3
	v_add_f32_e32 v89, 1.0, v89
	v_add_f32_e32 v144, 1.0, v144
	v_add_f32_e32 v145, 1.0, v145
	v_rcp_f32_e32 v3, v3
	v_rcp_f32_e32 v89, v89
	v_rcp_f32_e32 v144, v144
	v_rcp_f32_e32 v145, v145
	v_or_b32_e32 v146, 6, v2
	v_ashrrev_i32_e32 v147, 31, v146
	v_mul_f32_e32 v1, v1, v3
	v_mul_f32_e32 v3, v88, v89
	v_mul_f32_e32 v89, v90, v144
	v_mul_f32_e32 v90, v91, v145
	v_cvt_pk_bf16_f32 v89, v89, v90
	v_lshlrev_b64 v[90:91], 10, v[146:147]
	v_lshl_add_u64 v[90:91], v[134:135], 0, v[90:91]
	v_cvt_pk_bf16_f32 v88, v1, v3
	global_store_dwordx2 v[90:91], v[88:89], off
.LBB0_660:
	s_or_b64 exec, exec, s[26:27]
	s_nop 4
	ds_read_b128 v[88:91], v105 offset:61440
	ds_read_b128 v[144:147], v105 offset:62464
	s_waitcnt lgkmcnt(1)
	v_mfma_f32_16x16x32_bf16 v[56:59], v[88:91], v[56:59], 0
	ds_read_b128 v[88:91], v105 offset:63488
	s_waitcnt lgkmcnt(1)
	v_mfma_f32_16x16x32_bf16 v[52:55], v[144:147], v[52:55], v[56:59]
	s_nop 4
	ds_read_b128 v[56:59], v105 offset:64512
	s_waitcnt lgkmcnt(1)
	v_mfma_f32_16x16x32_bf16 v[52:55], v[88:91], v[64:67], v[52:55]
	ds_read_b128 v[64:67], v192
	s_waitcnt lgkmcnt(1)
	v_mfma_f32_16x16x32_bf16 v[52:55], v[56:59], v[60:63], v[52:55]
	ds_read_b128 v[56:59], v193
	ds_read_b128 v[60:63], v194
	s_waitcnt lgkmcnt(2)
	v_mfma_f32_16x16x32_bf16 v[52:55], v[64:67], v[72:75], v[52:55]
	s_waitcnt lgkmcnt(1)
	v_mfma_f32_16x16x32_bf16 v[52:55], v[56:59], v[80:83], v[52:55]
	ds_read_b128 v[56:59], v195
	s_waitcnt lgkmcnt(1)
	v_mfma_f32_16x16x32_bf16 v[52:55], v[60:63], v[68:71], v[52:55]
	s_waitcnt lgkmcnt(0)
	v_mfma_f32_16x16x32_bf16 v[52:55], v[56:59], v[76:79], v[52:55]
	s_and_saveexec_b64 s[26:27], s[24:25]
	s_cbranch_execz .LBB0_662
	v_lshlrev_b32_e32 v1, 16, v142
	s_nop 0
	s_nop 3
	v_fma_f32 v1, v228, v1, v52
	v_mul_f32_e32 v3, v1, v1
	v_fmamk_f32 v3, v3, 0xbdd2d3e8, v93
	v_mul_f32_e32 v3, v1, v3
	v_exp_f32_e32 v52, v3
	v_and_b32_e32 v3, 0xffff0000, v142
	v_lshlrev_b32_e32 v57, 16, v143
	v_fma_f32 v53, v229, v3, v53
	v_fma_f32 v54, v230, v57, v54
	v_and_b32_e32 v58, 0xffff0000, v143
	v_mul_f32_e32 v3, v53, v53
	v_mul_f32_e32 v57, v54, v54
	v_fmac_f32_e32 v55, v231, v58
	v_fmamk_f32 v3, v3, 0xbdd2d3e8, v93
	v_fmamk_f32 v57, v57, 0xbdd2d3e8, v93
	v_mul_f32_e32 v58, v55, v55
	v_mul_f32_e32 v3, v53, v3
	v_mul_f32_e32 v57, v54, v57
	v_fmamk_f32 v58, v58, 0xbdd2d3e8, v93
	v_exp_f32_e32 v56, v3
	v_exp_f32_e32 v57, v57
	v_mul_f32_e32 v58, v55, v58
	v_exp_f32_e32 v58, v58
	v_add_f32_e32 v52, 1.0, v52
	v_add_f32_e32 v56, 1.0, v56
	v_add_f32_e32 v57, 1.0, v57
	v_rcp_f32_e32 v52, v52
	v_rcp_f32_e32 v56, v56
	v_rcp_f32_e32 v57, v57
	v_add_f32_e32 v58, 1.0, v58
	v_or_b32_e32 v2, 7, v2
	v_rcp_f32_e32 v58, v58
	v_ashrrev_i32_e32 v3, 31, v2
	v_lshlrev_b64 v[2:3], 10, v[2:3]
	v_mul_f32_e32 v1, v1, v52
	v_mul_f32_e32 v52, v53, v56
	v_mul_f32_e32 v53, v54, v57
	v_lshl_add_u64 v[2:3], v[134:135], 0, v[2:3]
	v_mul_f32_e32 v54, v55, v58
	v_cvt_pk_bf16_f32 v52, v1, v52
	v_cvt_pk_bf16_f32 v53, v53, v54
	global_store_dwordx2 v[2:3], v[52:53], off
